# pool-GEMM residual epilogue: gate and pool-scale loads issued together, one wait (was four serialized load/wait/mul groups)
# speedup vs baseline: 1.0085x; 1.0010x over previous
;     __device__ __forceinline__ void operator()(const f32x4 (&acc)[2][2][4][2], const Unit& u, int wr, int wc, int fr_, int fq_) const {
;     ...
;         const int row0 = u.pm * BM + wr * 64 + fr, col0 = u.grp * gcols + u.pn * BM + wc * 32 + 8 * fq;
;         const int rowt = u.pm * BM; const int bidx = rowt < mlat ? (rowt >> 12) : 4;
;         const float* gp = gate + (size_t)bidx * gstride + col0;
;         f32x4 gv[2][2];
; #pragma unroll
;         for (int bj = 0; bj < 2; ++bj)
; #pragma unroll
;             for (int n = 0; n < 2; ++n) { gv[bj][n] = *(const f32x4*)(gp + bj * HALF + n * 4); if (cscale) gv[bj][n] = gv[bj][n] * *(const f32x4*)(cscale + col0 + bj * HALF + n * 4); }
.LBB0_429:
	s_lshl_b32 s1, s4, 9
	s_lshl_b32 s4, s10, 8
	s_or_b32 s1, s1, s74
	v_mov_b32_e32 v60, v250
	v_mov_b32_e32 v102, v249
	s_add_i32 s1, s1, s4
	s_nop 0
	v_lshl_add_u32 v140, v60, 3, s1
	s_min_i32 s1, s0, 64
	s_ashr_i32 s1, s1, 4
	s_mul_hi_i32 s5, s1, 0xc000
	s_mul_i32 s1, s1, 0xc000
	s_add_u32 s4, s71, s1
	v_ashrrev_i32_e32 v141, 31, v140
	s_addc_u32 s5, s72, s5
	v_lshlrev_b64 v[60:61], 2, v[140:141]
	v_lshl_add_u64 v[64:65], s[4:5], 0, v[60:61]
	global_load_dwordx4 v[68:71], v[64:65], off
	v_lshl_add_u64 v[100:101], s[46:47], 0, v[60:61]
	v_cndmask_b32_e64 v60, 0, 1, s[50:51]
	v_cmp_ne_u32_e64 s[4:5], 1, v60
	global_load_dwordx4 v[72:75], v[64:65], off offset:16
	s_nop 1
	global_load_dwordx4 v[60:63], v[64:65], off offset:512
	global_load_dwordx4 v[64:67], v[64:65], off offset:528
	s_andn2_b64 vcc, exec, s[50:51]
	v_readlane_b32 s16, v255, 14
	v_readlane_b32 s17, v255, 15
	s_cbranch_vccnz .LBB0_437
	global_load_dwordx4 v[184:187], v[100:101], off
	global_load_dwordx4 v[188:191], v[100:101], off offset:16
	global_load_dwordx4 v[192:195], v[100:101], off offset:512
	global_load_dwordx4 v[196:199], v[100:101], off offset:528
	s_waitcnt vmcnt(0)
	v_pk_mul_f32 v[70:71], v[70:71], v[186:187]
	v_pk_mul_f32 v[68:69], v[68:69], v[184:185]
	v_pk_mul_f32 v[74:75], v[74:75], v[190:191]
	v_pk_mul_f32 v[72:73], v[72:73], v[188:189]
	v_pk_mul_f32 v[62:63], v[62:63], v[194:195]
	v_pk_mul_f32 v[60:61], v[60:61], v[192:193]
	v_pk_mul_f32 v[66:67], v[66:67], v[198:199]
	v_pk_mul_f32 v[64:65], v[64:65], v[196:197]
